# attention: the two waves of each SIMD run at different priorities (waves 0-3 prio 3, waves 4-7 prio 2)
# speedup vs baseline: 1.0216x; 1.0084x over previous
; __device__ __forceinline__ void attn_phase(int wv, const bf16_t* Q, const bf16_t* Kf, const bf16_t* Vt, const bf16_t* proj, bf16_t* mixed, LAS unsigned char* lds) { LIDS
;     ...
;     if (wid >= 4) __builtin_amdgcn_s_setprio(1);
;     ...
;             for (int t = 0; t < nt; ++t) {
;                 const int b = t & 1;
;                 asm volatile("s_waitcnt vmcnt(0)" ::: "memory"); __builtin_amdgcn_s_barrier(); asm volatile("" ::: "memory");
;                 if (t + 1 < nt) ATT_ISSUE(t + 1, b ^ 1);
.Lp2_loop0:
	s_waitcnt vmcnt(0)
	s_barrier
	s_setprio 3
	s_cmp_lt_u32 s3, 4
	s_cbranch_scc1 .Lp2_pr
	s_setprio 2
.Lp2_pr:
	s_add_i32 s22, s19, 2
	s_add_i32 s24, s19, 1
	s_cmp_gt_i32 s19, s21
	s_cbranch_scc1 .Lp2_idle0
	s_cmp_eq_u32 s19, s21
	s_cbranch_scc1 .Lp2_drain0
	ds_read_b128 v[160:163], v207 offset:0xa010
	ds_read_b128 v[164:167], v207 offset:0xd010
	ds_read_b128 v[168:171], v208 offset:0xa010
	ds_read_b128 v[172:175], v208 offset:0xd010
